# PEER table quantisation row loops (fp6/fp4): next row prefetched into spare registers at loop top, counted wait; near s_endpgm for two far exits
# speedup vs baseline: 1.0143x; 1.0030x over previous
; #define LAS __attribute__((address_space(3)))
; __global__ void __launch_bounds__(256, 2) mega_kernel(Params P, int ph_lo, int ph_hi) {
;   __shared__ __attribute__((aligned(16))) char smem[73728];
;   __shared__ uint4 xb_words;
;   if (threadIdx.x == 0) xb_words = make_uint4(0u, 0u, 0u, 0u);
;   __syncthreads();
;   XcdBarrier xb = xcd_barrier_post(P.bar, (volatile LAS unsigned*)&xb_words);
;   for (int ph = ph_lo; ph < ph_hi; ++ph) {
.LBB0_5:
	s_or_b64 exec, exec, s[10:11]
	s_load_dwordx2 s[4:5], s[0:1], 0x1d0
	s_waitcnt lgkmcnt(0)
	v_writelane_b32 v251, s4, 8
	s_nop 1
	v_writelane_b32 v251, s5, 9
	s_cmp_ge_i32 s4, s5
	s_cbranch_scc1 .Lend_near
	s_load_dwordx4 s[60:63], s[0:1], 0x160
	s_load_dwordx8 s[24:31], s[0:1], 0x140
	s_load_dwordx16 s[8:23], s[0:1], 0x0
	s_mov_b32 s4, s2
	s_mov_b32 s3, 0
	v_lshrrev_b32_e32 v1, 20, v0
	v_lshrrev_b32_e32 v0, 10, v0
	s_waitcnt lgkmcnt(0)
	v_writelane_b32 v251, s8, 10
	v_or_b32_e32 v0, v0, v1
	v_mov_b32_e32 v177, 0
	v_writelane_b32 v251, s9, 11
	v_writelane_b32 v251, s10, 12
	v_writelane_b32 v251, s11, 13
	v_writelane_b32 v251, s12, 14
	v_writelane_b32 v251, s13, 15
	v_writelane_b32 v251, s14, 16
	v_writelane_b32 v251, s15, 17
	v_writelane_b32 v251, s16, 18
	v_writelane_b32 v251, s17, 19
	v_writelane_b32 v251, s18, 20
	v_writelane_b32 v251, s19, 21
	v_writelane_b32 v251, s20, 22
	v_writelane_b32 v251, s21, 23
	v_writelane_b32 v251, s22, 24
	v_writelane_b32 v251, s23, 25
	s_load_dwordx16 s[8:23], s[0:1], 0x40
	s_mov_b32 s34, 0x42000000
	s_movk_i32 s65, 0x2000
	v_mov_b32_e32 v203, 0x3727c5ac
	s_movk_i32 s67, 0x110
	s_waitcnt lgkmcnt(0)
	v_writelane_b32 v251, s8, 26
	v_mov_b32_e32 v204, 0x11ff0
	s_mov_b32 s66, 0xefa18f08
	v_writelane_b32 v251, s9, 27
	v_writelane_b32 v251, s10, 28
	v_writelane_b32 v251, s11, 29
	v_writelane_b32 v251, s12, 30
	v_writelane_b32 v251, s13, 31
	v_writelane_b32 v251, s14, 32
	v_writelane_b32 v251, s15, 33
	v_writelane_b32 v251, s16, 34
	v_writelane_b32 v251, s17, 35
	v_writelane_b32 v251, s18, 36
	v_writelane_b32 v251, s19, 37
	v_writelane_b32 v251, s20, 38
	v_writelane_b32 v251, s21, 39
	v_writelane_b32 v251, s22, 40
	v_writelane_b32 v251, s23, 41
	s_load_dwordx16 s[84:99], s[0:1], 0x80
	s_load_dwordx16 s[36:51], s[0:1], 0xc0
	s_load_dwordx16 s[68:83], s[0:1], 0x100
	s_load_dwordx16 s[8:23], s[0:1], 0x178
	s_add_u32 s0, s0, 0x1d8
	s_addc_u32 s1, s1, 0
	s_cmpk_lt_i32 s2, 0x2000
	s_mov_b32 s35, 0x42040000
	s_waitcnt lgkmcnt(0)
	v_writelane_b32 v251, s8, 42
	v_mov_b32_e32 v205, 0x3ecc95a3
	v_mov_b32_e32 v206, 0x260
	v_writelane_b32 v251, s9, 43
	v_writelane_b32 v251, s10, 44
	v_writelane_b32 v251, s11, 45
	v_writelane_b32 v251, s12, 46
	v_writelane_b32 v251, s13, 47
	v_writelane_b32 v251, s14, 48
	v_writelane_b32 v251, s15, 49
	v_writelane_b32 v251, s16, 50
	v_writelane_b32 v251, s17, 51
	v_writelane_b32 v251, s18, 52
	v_writelane_b32 v251, s19, 53
	v_writelane_b32 v251, s20, 54
	v_writelane_b32 v251, s21, 55
	v_writelane_b32 v251, s22, 56
	v_writelane_b32 v251, s23, 57
	v_writelane_b32 v251, s0, 58
	v_mov_b32_e32 v207, 0x12000
	v_mov_b32_e32 v208, 0x12004
	v_writelane_b32 v251, s1, 59
	s_cselect_b64 s[0:1], -1, 0
	v_writelane_b32 v251, s0, 60
	v_mov_b32_e32 v209, 1
	v_mov_b32_e32 v210, 0x3a800000
	v_writelane_b32 v251, s1, 61
	s_lshl_b32 s0, s2, 2
	v_writelane_b32 v251, s0, 62
	s_and_b32 s0, s2, 7
	s_ashr_i32 s2, s2, 3
	s_xor_b32 s1, s0, 7
	s_cmpk_lt_i32 s2, 0x100
	s_cselect_b64 s[8:9], -1, 0
	s_lshl_b32 s7, s0, 12
	v_writelane_b32 v252, s8, 0
	s_bitcmp0_b32 s4, 8
	v_writelane_b32 v251, s1, 63
	v_writelane_b32 v252, s9, 1
	s_cselect_b64 s[0:1], -1, 0
	v_writelane_b32 v252, s0, 2
	s_ashr_i32 s5, s4, 31
	v_readlane_b32 s8, v251, 10
	v_writelane_b32 v252, s1, 3
	s_lshl_b64 s[0:1], s[4:5], 8
	v_writelane_b32 v252, s0, 4
	v_readlane_b32 s10, v251, 12
	v_readlane_b32 s11, v251, 13
	v_writelane_b32 v252, s1, 5
	s_add_u32 s0, s10, 0x918000
	s_addc_u32 s1, s11, 0
	v_writelane_b32 v252, s0, 6
	v_readlane_b32 s9, v251, 11
	v_readlane_b32 s12, v251, 14
	v_writelane_b32 v252, s1, 7
	s_add_u32 s0, s68, 0x4c0000
	s_addc_u32 s1, s69, 0
	v_writelane_b32 v252, s0, 8
	v_readlane_b32 s13, v251, 15
	v_readlane_b32 s14, v251, 16
	v_writelane_b32 v252, s1, 9
	s_add_u32 s0, s96, 0x400000
	s_addc_u32 s1, s97, 0
	s_add_u32 s8, s70, 0x200000
	s_addc_u32 s9, s71, 0
	v_writelane_b32 v252, s8, 10
	v_readlane_b32 s15, v251, 17
	v_readlane_b32 s16, v251, 18
	v_writelane_b32 v252, s9, 11
	v_writelane_b32 v252, s36, 12
	s_add_u32 s8, s38, 0x800000
	s_addc_u32 s9, s39, 0
	v_writelane_b32 v252, s37, 13
	v_writelane_b32 v252, s38, 14
	v_writelane_b32 v252, s39, 15
	v_writelane_b32 v252, s40, 16
	v_writelane_b32 v252, s41, 17
	v_writelane_b32 v252, s42, 18
	v_writelane_b32 v252, s43, 19
	v_writelane_b32 v252, s44, 20
	v_writelane_b32 v252, s45, 21
	v_writelane_b32 v252, s46, 22
	v_writelane_b32 v252, s47, 23
	v_writelane_b32 v252, s48, 24
	v_writelane_b32 v252, s49, 25
	v_writelane_b32 v252, s50, 26
	v_writelane_b32 v252, s51, 27
	v_writelane_b32 v252, s8, 28
	v_readlane_b32 s17, v251, 19
	v_readlane_b32 s18, v251, 20
	v_writelane_b32 v252, s9, 29
	s_add_u32 s8, s72, 0x400000
	s_addc_u32 s9, s73, 0
	v_writelane_b32 v252, s8, 30
	v_readlane_b32 s19, v251, 21
	v_readlane_b32 s20, v251, 22
	v_writelane_b32 v252, s9, 31
	s_add_u32 s8, s76, 0x80000
	s_addc_u32 s9, s77, 0
	v_readlane_b32 s21, v251, 23
	v_readlane_b32 s22, v251, 24
	v_readlane_b32 s23, v251, 25
	v_writelane_b32 v252, s8, 32
	s_mov_b32 s5, s3
	v_mov_b32_e32 v211, 0x47f12065
	v_writelane_b32 v252, s9, 33
	v_readlane_b32 s8, v251, 26
	v_readlane_b32 s14, v251, 32
	v_readlane_b32 s9, v251, 27
	v_readlane_b32 s15, v251, 33
	s_add_u32 s8, s14, 0x80000
	s_addc_u32 s9, s15, 0
	v_writelane_b32 v252, s8, 34
	v_readlane_b32 s10, v251, 28
	v_readlane_b32 s12, v251, 30
	v_writelane_b32 v252, s9, 35
	s_add_u32 s8, s84, 0x80000
	v_writelane_b32 v252, s84, 36
	s_addc_u32 s9, s85, 0
	v_readlane_b32 s13, v251, 31
	v_writelane_b32 v252, s85, 37
	v_writelane_b32 v252, s86, 38
	v_writelane_b32 v252, s87, 39
	v_writelane_b32 v252, s88, 40
	v_writelane_b32 v252, s89, 41
	v_writelane_b32 v252, s90, 42
; #define LAS __attribute__((address_space(3)))
; __global__ void __launch_bounds__(256, 2) mega_kernel(Params P, int ph_lo, int ph_hi) {
;   __shared__ __attribute__((aligned(16))) char smem[73728];
;   __shared__ uint4 xb_words;
;   if (threadIdx.x == 0) xb_words = make_uint4(0u, 0u, 0u, 0u);
;   __syncthreads();
;   XcdBarrier xb = xcd_barrier_post(P.bar, (volatile LAS unsigned*)&xb_words);
;   for (int ph = ph_lo; ph < ph_hi; ++ph) {
;     const int nrep = (ph == PROBE_DUP) ? 2 : 1;
; #pragma unroll 1
;     for (int rep = 0; rep < nrep; ++rep) { run_phase(P, ph, smem, rep + 1 == nrep); __syncthreads(); }
;     if (ph + 1 < ph_hi) {
;       if (ph_hi > 1000) cg::this_grid().sync();
;       if (ph == 0 || ((ph - 1) & 7) != 6) xcd_barrier(xb);
;     }
;   }
; }
	v_writelane_b32 v252, s91, 43
	v_writelane_b32 v252, s92, 44
	v_writelane_b32 v252, s93, 45
	v_writelane_b32 v252, s94, 46
	v_writelane_b32 v252, s95, 47
	v_writelane_b32 v252, s96, 48
	v_writelane_b32 v252, s97, 49
	v_writelane_b32 v252, s98, 50
	v_writelane_b32 v252, s99, 51
	s_mov_b64 s[98:99], s[0:1]
	v_writelane_b32 v252, s8, 52
	s_add_u32 s0, s76, 0xc0000
	s_addc_u32 s1, s77, 0
	v_writelane_b32 v252, s9, 53
	v_writelane_b32 v252, s0, 54
	s_cmpk_lt_u32 s4, 0x400
	v_readlane_b32 s8, v251, 0
	v_writelane_b32 v252, s1, 55
	s_cselect_b64 s[0:1], -1, 0
	v_writelane_b32 v252, s0, 56
	s_lshr_b32 s10, s4, 3
	v_readlane_b32 s9, v251, 1
	v_writelane_b32 v252, s1, 57
	s_add_u32 s0, s8, 0x3600
	v_writelane_b32 v252, s0, 58
	s_addc_u32 s0, s9, 0
	s_cmpk_lt_i32 s4, 0x600
	v_writelane_b32 v252, s0, 59
	s_cselect_b64 s[0:1], -1, 0
	v_writelane_b32 v252, s0, 60
	s_cmpk_lt_u32 s4, 0x980
	v_readlane_b32 s11, v251, 29
	v_writelane_b32 v252, s1, 61
	s_cselect_b64 s[0:1], -1, 0
	v_writelane_b32 v252, s0, 62
	v_readlane_b32 s16, v251, 34
	v_readlane_b32 s17, v251, 35
	v_writelane_b32 v252, s1, 63
	s_lshl_b64 s[0:1], s[4:5], 8
	v_writelane_b32 v250, s0, 0
	v_readlane_b32 s18, v251, 36
	v_readlane_b32 s19, v251, 37
	v_writelane_b32 v250, s1, 1
	s_add_u32 s0, s76, 0x40000
	s_addc_u32 s1, s77, 0
	v_writelane_b32 v250, s0, 2
	v_readlane_b32 s20, v251, 38
	v_readlane_b32 s21, v251, 39
	v_writelane_b32 v250, s1, 3
	v_readlane_b32 s0, v251, 8
	v_readlane_b32 s1, v251, 9
	s_cmpk_gt_i32 s1, 0x3e8
	s_cselect_b64 s[0:1], -1, 0
	v_writelane_b32 v250, s0, 4
	v_readlane_b32 s22, v251, 40
	v_readlane_b32 s23, v251, 41
	v_writelane_b32 v250, s1, 5
	s_movk_i32 s0, 0x3ff
	v_and_or_b32 v0, v0, s0, v202
	v_cmp_eq_u32_e64 s[0:1], 0, v0
	v_readlane_b32 s36, v252, 12
	v_readlane_b32 s40, v252, 16
	v_writelane_b32 v250, s0, 6
	v_readlane_b32 s41, v252, 17
	s_mov_b32 s84, 0x41900000
	v_writelane_b32 v250, s1, 7
	s_add_u32 s0, s8, 0x200
	s_addc_u32 s1, s9, 0
	v_writelane_b32 v250, s0, 8
	s_mov_b32 s86, 0x42480000
	s_mov_b32 s88, 0x41a00000
	v_writelane_b32 v250, s1, 9
	s_add_u32 s0, s8, 0x1000
	s_addc_u32 s1, s9, 0
	v_writelane_b32 v250, s0, 10
	s_mov_b32 s90, 0x42500000
	s_mov_b32 s92, 0x41b00000
	v_writelane_b32 v250, s1, 11
	s_add_u32 s0, s8, 0x1100
	s_addc_u32 s1, s9, 0
	v_writelane_b32 v250, s0, 12
	s_mov_b32 s94, 0x42580000
	v_mbcnt_lo_u32_b32 v0, -1, 0
	v_writelane_b32 v250, s1, 13
	s_add_u32 s0, s8, 0x1200
	s_addc_u32 s1, s9, 0
	v_writelane_b32 v250, s0, 14
	s_movk_i32 s97, 0x4000
	s_mov_b32 s36, 0x3e38aa3b
	v_writelane_b32 v250, s1, 15
	s_add_u32 s0, s8, 0x1300
	s_addc_u32 s1, s9, 0
	v_writelane_b32 v250, s0, 16
	s_cmp_eq_u32 s6, 15
	s_mov_b32 s85, 0x41980000
	v_writelane_b32 v250, s1, 17
	s_cselect_b64 s[0:1], -1, 0
	v_writelane_b32 v250, s0, 18
	s_cmp_eq_u32 s6, 14
	s_mov_b32 s87, 0x424c0000
	v_writelane_b32 v250, s1, 19
	s_cselect_b64 s[0:1], -1, 0
	v_writelane_b32 v250, s0, 20
	s_cmp_eq_u32 s6, 13
	s_mov_b32 s89, 0x41a80000
	v_writelane_b32 v250, s1, 21
	s_cselect_b64 s[0:1], -1, 0
	v_writelane_b32 v250, s0, 22
	s_cmp_eq_u32 s6, 12
	s_mov_b32 s91, 0x42540000
	v_writelane_b32 v250, s1, 23
	s_cselect_b64 s[0:1], -1, 0
	v_writelane_b32 v250, s0, 24
	s_cmp_eq_u32 s6, 11
	s_mov_b32 s93, 0x41b80000
	v_writelane_b32 v250, s1, 25
	s_cselect_b64 s[0:1], -1, 0
	v_writelane_b32 v250, s0, 26
	s_cmp_eq_u32 s6, 10
	s_mov_b32 s95, 0x425c0000
	v_writelane_b32 v250, s1, 27
	s_cselect_b64 s[0:1], -1, 0
	v_writelane_b32 v250, s0, 28
	s_cmp_eq_u32 s6, 9
	v_mbcnt_hi_u32_b32 v212, -1, v0
	v_writelane_b32 v250, s1, 29
	s_cselect_b64 s[0:1], -1, 0
	v_writelane_b32 v250, s0, 30
	s_cmp_eq_u32 s6, 8
	v_bfrev_b32_e32 v213, 1
	v_writelane_b32 v250, s1, 31
	s_cselect_b64 s[0:1], -1, 0
	v_writelane_b32 v250, s0, 32
	s_cmp_eq_u32 s6, 7
	v_mov_b32_e32 v214, 0x42800000
	v_writelane_b32 v250, s1, 33
	s_cselect_b64 s[0:1], -1, 0
	v_writelane_b32 v250, s0, 34
	s_cmp_eq_u32 s6, 6
	v_not_b32_e32 v215, 63
	v_writelane_b32 v250, s1, 35
	s_cselect_b64 s[0:1], -1, 0
	v_writelane_b32 v250, s0, 36
	s_cmp_eq_u32 s6, 5
	v_mov_b32_e32 v178, 0x3e000000
	v_writelane_b32 v250, s1, 37
	s_cselect_b64 s[0:1], -1, 0
	v_writelane_b32 v250, s0, 38
	s_cmp_eq_u32 s6, 4
	v_mov_b32_e32 v216, 0xf149f2ca
	v_writelane_b32 v250, s1, 39
	s_cselect_b64 s[0:1], -1, 0
	v_writelane_b32 v250, s0, 40
	s_cmp_eq_u32 s6, 3
	v_mov_b32_e32 v217, 0xffffff80
	v_writelane_b32 v250, s1, 41
	s_cselect_b64 s[0:1], -1, 0
	v_writelane_b32 v250, s0, 42
	s_cmp_eq_u32 s6, 2
; #define LAS __attribute__((address_space(3)))
; __global__ void __launch_bounds__(256, 2) mega_kernel(Params P, int ph_lo, int ph_hi) {
;   __shared__ __attribute__((aligned(16))) char smem[73728];
;   __shared__ uint4 xb_words;
;   if (threadIdx.x == 0) xb_words = make_uint4(0u, 0u, 0u, 0u);
;   __syncthreads();
;   XcdBarrier xb = xcd_barrier_post(P.bar, (volatile LAS unsigned*)&xb_words);
;   for (int ph = ph_lo; ph < ph_hi; ++ph) {
;     const int nrep = (ph == PROBE_DUP) ? 2 : 1;
; #pragma unroll 1
;     for (int rep = 0; rep < nrep; ++rep) { run_phase(P, ph, smem, rep + 1 == nrep); __syncthreads(); }
;     if (ph + 1 < ph_hi) {
;       if (ph_hi > 1000) cg::this_grid().sync();
;       if (ph == 0 || ((ph - 1) & 7) != 6) xcd_barrier(xb);
;     }
;   }
; }
	v_mov_b32_e32 v218, 0x7149f2ca
	v_writelane_b32 v250, s1, 43
	s_cselect_b64 s[0:1], -1, 0
	v_writelane_b32 v250, s0, 44
	s_cmp_eq_u32 s6, 1
	v_mov_b32_e32 v219, 0xff61b1e6
	v_writelane_b32 v250, s1, 45
	s_cselect_b64 s[0:1], -1, 0
	v_writelane_b32 v250, s0, 46
	s_cmp_eq_u32 s6, 0
	v_mov_b32_e32 v220, 0x3b000000
	v_writelane_b32 v250, s1, 47
	s_cselect_b64 s[0:1], -1, 0
	v_writelane_b32 v250, s0, 48
	v_mov_b32_e32 v221, 0x1030
	v_mov_b32_e32 v222, 0x7f800000
	v_writelane_b32 v250, s1, 49
	s_lshl_b32 s0, s6, 8
	s_add_u32 s0, s8, s0
	s_addc_u32 s1, s9, 0
	s_add_u32 s12, s0, 0x1400
	s_addc_u32 s13, s1, 0
	v_writelane_b32 v250, s12, 50
	s_add_u32 s0, s0, 0x2400
	s_addc_u32 s1, s1, 0
	v_writelane_b32 v250, s13, 51
	v_writelane_b32 v250, s0, 52
	v_mov_b32_e32 v223, 0x7fc00000
	v_mov_b32_e32 v224, 0xff800000
	v_writelane_b32 v250, s1, 53
	s_add_u32 s0, s8, 0x3400
	s_addc_u32 s1, s9, 0
	v_writelane_b32 v250, s0, 54
	v_mov_b32_e32 v225, 0x4000
	v_mov_b32_e32 v234, v177
	v_writelane_b32 v250, s1, 55
	s_add_u32 s0, s8, 0x3500
	s_addc_u32 s1, s9, 0
	v_writelane_b32 v250, s0, 56
	v_mov_b32_e32 v235, v177
	v_mov_b32_e32 v236, v177
	v_writelane_b32 v250, s1, 57
	v_writelane_b32 v250, s2, 58
	s_lshl_b32 s0, s2, 4
	v_writelane_b32 v250, s7, 59
	s_add_i32 s0, s7, s0
	v_writelane_b32 v250, s0, 60
	v_writelane_b32 v250, s10, 61
	s_lshl_b32 s0, s10, 7
	v_writelane_b32 v250, s0, 62
	s_add_i32 s0, s4, 0xfffffe00
	v_writelane_b32 v250, s0, 63
	s_lshl_b32 s0, s4, 8
	s_add_i32 s0, s0, 0xfffe0000
	v_writelane_b32 v249, s0, 0
	s_lshl_b32 s0, s4, 4
	v_writelane_b32 v249, s0, 1
	s_lshl_b32 s0, s4, 3
	v_writelane_b32 v249, s0, 2
	s_lshl_b64 s[0:1], s[4:5], 13
	s_or_b32 s0, s0, 16
	v_readlane_b32 s8, v251, 10
	v_readlane_b32 s9, v251, 11
	s_add_u32 s6, s8, s0
	s_addc_u32 s7, s9, s1
	v_writelane_b32 v249, s6, 3
	s_mov_b32 s2, s4
	s_lshl_b64 s[4:5], s[4:5], 12
	v_writelane_b32 v249, s7, 4
	v_writelane_b32 v249, s2, 5
	v_readlane_b32 s10, v251, 12
	v_readlane_b32 s11, v251, 13
	v_writelane_b32 v249, s3, 6
	s_or_b32 s2, s4, 8
	s_add_u32 s6, s28, s2
	s_addc_u32 s7, s29, s5
	v_writelane_b32 v249, s6, 7
	s_add_u32 s0, s40, s0
	s_addc_u32 s1, s41, s1
	v_writelane_b32 v249, s7, 8
	v_writelane_b32 v249, s0, 9
	v_readlane_b32 s12, v251, 14
	v_readlane_b32 s13, v251, 15
	v_writelane_b32 v249, s1, 10
	s_add_u32 s0, s74, s2
	s_addc_u32 s1, s75, s5
	v_writelane_b32 v249, s0, 11
	v_readlane_b32 s14, v251, 16
	v_readlane_b32 s15, v251, 17
	v_writelane_b32 v249, s1, 12
	s_add_u32 s0, s78, s2
	s_addc_u32 s1, s79, s5
	v_writelane_b32 v249, s0, 13
	v_readlane_b32 s16, v251, 18
	v_readlane_b32 s17, v251, 19
	v_writelane_b32 v249, s1, 14
	v_writelane_b32 v249, s60, 15
	v_readlane_b32 s18, v251, 20
	v_readlane_b32 s19, v251, 21
	v_writelane_b32 v249, s61, 16
	v_writelane_b32 v249, s62, 17
	v_writelane_b32 v249, s63, 18
	v_writelane_b32 v249, s98, 19
	v_readlane_b32 s20, v251, 22
	v_readlane_b32 s21, v251, 23
	v_writelane_b32 v249, s99, 20
	v_writelane_b32 v249, s68, 21
	v_readlane_b32 s22, v251, 24
	v_readlane_b32 s23, v251, 25
	v_writelane_b32 v249, s69, 22
	v_writelane_b32 v249, s70, 23
	v_writelane_b32 v249, s71, 24
	v_writelane_b32 v249, s72, 25
	v_writelane_b32 v249, s73, 26
	v_writelane_b32 v249, s74, 27
	v_writelane_b32 v249, s75, 28
	v_writelane_b32 v249, s76, 29
	v_writelane_b32 v249, s77, 30
	v_writelane_b32 v249, s78, 31
	v_writelane_b32 v249, s79, 32
	v_writelane_b32 v249, s80, 33
	s_mov_b32 s12, 2.0
	s_mov_b32 s8, 0x42080000
	s_mov_b32 s10, 4.0
	s_mov_b32 s14, 0x42100000
	s_mov_b32 s16, 0x40c00000
	s_mov_b32 s18, 0x42180000
	s_mov_b32 s20, 0x41800000
	s_mov_b32 s22, 0x42400000
	v_writelane_b32 v249, s81, 34
	s_mov_b32 s13, 0x40400000
	s_mov_b32 s9, 0x420c0000
	s_mov_b32 s11, 0x40a00000
	s_mov_b32 s15, 0x42140000
	s_mov_b32 s17, 0x40e00000
	s_mov_b32 s19, 0x421c0000
	s_mov_b32 s21, 0x41880000
	s_mov_b32 s23, 0x42440000
	v_mov_b32_e32 v237, v177
	v_writelane_b32 v249, s82, 35
	v_readlane_b32 s37, v252, 13
	v_readlane_b32 s38, v252, 14
	v_readlane_b32 s39, v252, 15
	v_readlane_b32 s42, v252, 18
	v_readlane_b32 s43, v252, 19
	v_readlane_b32 s44, v252, 20
	v_readlane_b32 s45, v252, 21
	v_readlane_b32 s46, v252, 22
	v_readlane_b32 s47, v252, 23
	v_readlane_b32 s48, v252, 24
	v_readlane_b32 s49, v252, 25
	v_readlane_b32 s50, v252, 26
	v_readlane_b32 s51, v252, 27
	v_writelane_b32 v249, s83, 36
	s_branch .LBB0_11
.Lend_near:
	s_endpgm
.LBB0_7:
	s_or_b64 exec, exec, s[40:41]
	s_waitcnt vmcnt(0)

; DEV int opaque_tid() { int t = (int)threadIdx.x; asm volatile("" : "+v"(t)); return t; }
; __device__ void quant_rows_fp6(const float* __restrict__ src, unsigned char* __restrict__ dst, float* __restrict__ scl, int nrows) {
;   const int tid = opaque_tid(), lane = tid & 63, w = tid >> 6;
;   const int l32 = lane & 31, hf = lane >> 5;
;   for (int rp = blockIdx.x * 4 + w; rp < nrows / 2; rp += gridDim.x * 4) {
;     const int r = rp * 2 + hf;
;     const float4* p = (const float4*)(src + (size_t)r * 1024 + l32 * 32);
;     float v[32];
; #pragma unroll
;     for (int i = 0; i < 8; ++i) { const float4 t = p[i]; v[4 * i] = t.x; v[4 * i + 1] = t.y; v[4 * i + 2] = t.z; v[4 * i + 3] = t.w; }
.LBB0_222:
	s_andn2_b64 vcc, exec, s[0:1]
	s_cbranch_vccnz .LBB0_309
	v_readlane_b32 s0, v249, 40
	s_cmp_lg_u32 s0, 1
	s_mov_b64 s[0:1], -1
	s_cbranch_scc0 .LBB0_283
	v_readlane_b32 s0, v248, 3
	v_readlane_b32 s1, v248, 4
	s_andn2_b64 vcc, exec, s[0:1]
	s_cbranch_vccnz .LBB0_236
	v_mov_b32_e32 v1, v202
	v_readlane_b32 s0, v251, 62
	v_ashrrev_i32_e32 v0, 6, v1
	s_nop 0
	v_add_u32_e32 v22, s0, v0
	v_cmp_gt_i32_e32 vcc, s97, v22
	s_and_saveexec_b64 s[0:1], vcc
	s_cbranch_execz .LBB0_230
	v_bfe_u32 v2, v1, 5, 1
	v_and_b32_e32 v1, 31, v1
	v_readlane_b32 s40, v252, 12
	v_lshlrev_b32_e32 v176, 7, v1
	v_readlane_b32 s41, v252, 13
	v_readlane_b32 s42, v252, 14
	v_readlane_b32 s43, v252, 15
	v_readlane_b32 s44, v252, 16
	v_readlane_b32 s45, v252, 17
	v_readlane_b32 s46, v252, 18
	v_readlane_b32 s47, v252, 19
	v_readlane_b32 s48, v252, 20
	v_readlane_b32 s49, v252, 21
	v_readlane_b32 s50, v252, 22
	v_readlane_b32 s51, v252, 23
	v_readlane_b32 s52, v252, 24
	v_readlane_b32 s53, v252, 25
	v_readlane_b32 s54, v252, 26
	v_readlane_b32 s55, v252, 27
	v_lshl_add_u64 v[16:17], s[46:47], 0, v[176:177]
	v_readlane_b32 s40, v251, 42
	v_and_b32_e32 v3, 64, v212
	v_readlane_b32 s41, v251, 43
	v_add_u32_e32 v3, 64, v3
	v_mul_u32_u24_e32 v176, 24, v1
	v_cmp_eq_u32_e64 s[40:41], 0, v1
	v_xor_b32_e32 v1, 1, v212
	v_cmp_lt_i32_e32 vcc, v1, v3
	v_readlane_b32 s4, v248, 34
	v_readlane_b32 s44, v251, 46
	v_cndmask_b32_e32 v1, v212, v1, vcc
	v_lshlrev_b32_e32 v23, 2, v1
	v_xor_b32_e32 v1, 2, v212
	v_cmp_lt_i32_e32 vcc, v1, v3
	v_readlane_b32 s45, v251, 47
	s_mov_b32 s6, s4
	v_cndmask_b32_e32 v1, v212, v1, vcc
	v_lshlrev_b32_e32 v24, 2, v1
	v_xor_b32_e32 v1, 4, v212
	v_cmp_lt_i32_e32 vcc, v1, v3
	s_lshl_b32 s2, s4, 2
	v_lshlrev_b32_e32 v0, 1, v0
	v_cndmask_b32_e32 v1, v212, v1, vcc
	v_lshlrev_b32_e32 v25, 2, v1
	v_xor_b32_e32 v1, 8, v212
	v_cmp_lt_i32_e32 vcc, v1, v3
	v_readlane_b32 s4, v249, 2
	v_lshl_add_u64 v[18:19], s[44:45], 0, v[176:177]
	v_cndmask_b32_e32 v1, v212, v1, vcc
	v_lshlrev_b32_e32 v26, 2, v1
	v_xor_b32_e32 v1, 16, v212
	v_cmp_lt_i32_e32 vcc, v1, v3
	v_add3_u32 v20, s4, v0, v2
	s_lshl_b32 s4, s6, 3
	v_cndmask_b32_e32 v1, v212, v1, vcc
	v_lshlrev_b32_e32 v27, 2, v1
	s_mov_b64 s[38:39], 0
	v_readlane_b32 s42, v251, 44
	v_readlane_b32 s43, v251, 45
	v_readlane_b32 s46, v251, 48
	v_readlane_b32 s47, v251, 49
	v_readlane_b32 s48, v251, 50
	v_readlane_b32 s49, v251, 51
	v_readlane_b32 s50, v251, 52
	v_readlane_b32 s51, v251, 53
	v_readlane_b32 s52, v251, 54
	v_readlane_b32 s53, v251, 55
	v_readlane_b32 s54, v251, 56
	v_readlane_b32 s55, v251, 57
	v_readlane_b32 s5, v248, 35
	v_ashrrev_i32_e32 v21, 31, v20
	v_lshlrev_b64 v[96:97], 12, v[20:21]
	v_lshl_add_u64 v[96:97], v[16:17], 0, v[96:97]
	global_load_dwordx4 v[64:67], v[96:97], off
	global_load_dwordx4 v[68:71], v[96:97], off offset:16
	global_load_dwordx4 v[72:75], v[96:97], off offset:32
	global_load_dwordx4 v[76:79], v[96:97], off offset:48
	global_load_dwordx4 v[80:83], v[96:97], off offset:64
	global_load_dwordx4 v[84:87], v[96:97], off offset:80
	global_load_dwordx4 v[88:91], v[96:97], off offset:96
	global_load_dwordx4 v[92:95], v[96:97], off offset:112
	s_waitcnt vmcnt(0)
	s_branch .Lq6a_copy

; __device__ void quant_rows_fp6(const float* __restrict__ src, unsigned char* __restrict__ dst, float* __restrict__ scl, int nrows) {
;     ...
;   for (int rp = blockIdx.x * 4 + w; rp < nrows / 2; rp += gridDim.x * 4) {
;     const int r = rp * 2 + hf;
;     const float4* p = (const float4*)(src + (size_t)r * 1024 + l32 * 32);
;     float v[32];
; #pragma unroll
;     for (int i = 0; i < 8; ++i) { const float4 t = p[i]; v[4 * i] = t.x; v[4 * i + 1] = t.y; v[4 * i + 2] = t.z; v[4 * i + 3] = t.w; }
;     float m = 0.f;
; #pragma unroll
;     for (int i = 0; i < 32; ++i) m = fmaxf(m, fabsf(v[i]));
; #pragma unroll
;     for (int o = 1; o < 32; o <<= 1) m = fmaxf(m, __shfl_xor(m, o, 64));
;     const float sc = (m > 0.f) ? m * (1.f / 7.5f) : 1.f;
;     const float inv = 1.f / sc;
;     v32bf_t bv;
; #pragma unroll
;     for (int i = 0; i < 32; ++i) bv[i] = (__bf16)(v[i] * inv);
;     const v6u_t qv = __builtin_amdgcn_cvt_scalef32_pk32_fp6_bf16(bv, 1.0f);
;     uint2* o2 = (uint2*)(dst + (size_t)r * 768 + l32 * 24);
;     uint2 t0, t1, t2; t0.x = qv[0]; t0.y = qv[1]; t1.x = qv[2]; t1.y = qv[3]; t2.x = qv[4]; t2.y = qv[5];
;     o2[0] = t0; o2[1] = t1; o2[2] = t2;
;     if (l32 == 0) scl[r] = sc;
;   }
.LBB0_228:
	s_waitcnt vmcnt(3)
.Lq6a_copy:
	v_pk_mov_b32 v[0:1], v[64:65], v[64:65] op_sel:[0,1]
	v_pk_mov_b32 v[2:3], v[66:67], v[66:67] op_sel:[0,1]
	v_pk_mov_b32 v[4:5], v[68:69], v[68:69] op_sel:[0,1]
	v_pk_mov_b32 v[6:7], v[70:71], v[70:71] op_sel:[0,1]
	v_pk_mov_b32 v[8:9], v[72:73], v[72:73] op_sel:[0,1]
	v_pk_mov_b32 v[10:11], v[74:75], v[74:75] op_sel:[0,1]
	v_pk_mov_b32 v[12:13], v[76:77], v[76:77] op_sel:[0,1]
	v_pk_mov_b32 v[14:15], v[78:79], v[78:79] op_sel:[0,1]
	v_pk_mov_b32 v[30:31], v[80:81], v[80:81] op_sel:[0,1]
	v_pk_mov_b32 v[32:33], v[82:83], v[82:83] op_sel:[0,1]
	v_pk_mov_b32 v[34:35], v[84:85], v[84:85] op_sel:[0,1]
	v_pk_mov_b32 v[36:37], v[86:87], v[86:87] op_sel:[0,1]
	v_pk_mov_b32 v[38:39], v[88:89], v[88:89] op_sel:[0,1]
	v_pk_mov_b32 v[40:41], v[90:91], v[90:91] op_sel:[0,1]
	v_pk_mov_b32 v[42:43], v[92:93], v[92:93] op_sel:[0,1]
	v_pk_mov_b32 v[44:45], v[94:95], v[94:95] op_sel:[0,1]
	v_add_u32_e32 v96, s4, v20
	v_min_i32_e32 v96, 0x7fff, v96
	v_ashrrev_i32_e32 v97, 31, v96
	v_lshlrev_b64 v[96:97], 12, v[96:97]
	v_lshl_add_u64 v[96:97], v[16:17], 0, v[96:97]
	global_load_dwordx4 v[64:67], v[96:97], off
	global_load_dwordx4 v[68:71], v[96:97], off offset:16
	global_load_dwordx4 v[72:75], v[96:97], off offset:32
	global_load_dwordx4 v[76:79], v[96:97], off offset:48
	global_load_dwordx4 v[80:83], v[96:97], off offset:64
	global_load_dwordx4 v[84:87], v[96:97], off offset:80
	global_load_dwordx4 v[88:91], v[96:97], off offset:96
	global_load_dwordx4 v[92:95], v[96:97], off offset:112
	v_ashrrev_i32_e32 v21, 31, v20
	s_movk_i32 s5, 0x300
	v_mad_i64_i32 v[46:47], s[6:7], v20, s5, v[18:19]
	v_max3_f32 v28, |v0|, 0, |v1|
	v_max3_f32 v28, v28, |v2|, |v3|
	v_max3_f32 v28, v28, |v4|, |v5|
	v_max3_f32 v28, v28, |v6|, |v7|
	v_max3_f32 v28, v28, |v8|, |v9|
	v_max3_f32 v28, v28, |v10|, |v11|
	v_max3_f32 v28, v28, |v12|, |v13|
	v_max3_f32 v28, v28, |v14|, |v15|
	v_max3_f32 v28, v28, |v30|, |v31|
	v_max3_f32 v28, v28, |v32|, |v33|
	v_max3_f32 v28, v28, |v34|, |v35|
	v_max3_f32 v28, v28, |v36|, |v37|
	v_max3_f32 v28, v28, |v38|, |v39|
	v_max3_f32 v28, v28, |v40|, |v41|
	v_max3_f32 v28, v28, |v42|, |v43|
	v_max3_f32 v28, v28, |v44|, |v45|
	ds_bpermute_b32 v29, v23, v28
	s_waitcnt lgkmcnt(0)
	v_max_f32_e32 v29, v29, v29
	v_max_f32_e32 v28, v28, v29
	ds_bpermute_b32 v29, v24, v28
	s_waitcnt lgkmcnt(0)
	v_max_f32_e32 v29, v29, v29
	v_max_f32_e32 v28, v28, v29
	ds_bpermute_b32 v29, v25, v28
	s_waitcnt lgkmcnt(0)
	v_max_f32_e32 v29, v29, v29
	v_max_f32_e32 v28, v28, v29
	ds_bpermute_b32 v29, v26, v28
	s_waitcnt lgkmcnt(0)
	v_max_f32_e32 v29, v29, v29
	v_max_f32_e32 v28, v28, v29
	ds_bpermute_b32 v29, v27, v28
	s_waitcnt lgkmcnt(0)
	v_max_f32_e32 v29, v29, v29
	v_max_f32_e32 v28, v28, v29
	v_mul_f32_e32 v29, 0x3e088889, v28
	v_cmp_lt_f32_e32 vcc, 0, v28
	s_nop 1
	v_cndmask_b32_e32 v28, 1.0, v29, vcc
	v_div_scale_f32 v29, s[6:7], v28, v28, 1.0
	v_rcp_f32_e32 v48, v29
	v_div_scale_f32 v49, vcc, 1.0, v28, 1.0
	v_fma_f32 v50, -v29, v48, 1.0
	v_fmac_f32_e32 v48, v50, v48
	v_mul_f32_e32 v50, v49, v48
	v_fma_f32 v51, -v29, v50, v49
	v_fmac_f32_e32 v50, v51, v48
	v_fma_f32 v29, -v29, v50, v49
	v_div_fmas_f32 v29, v29, v48, v50
	v_div_fixup_f32 v48, v29, v28, 1.0
	v_pk_mul_f32 v[0:1], v[0:1], v[48:49] op_sel_hi:[1,0]
	v_pk_mul_f32 v[2:3], v[2:3], v[48:49] op_sel_hi:[1,0]
	v_pk_mul_f32 v[4:5], v[4:5], v[48:49] op_sel_hi:[1,0]
	v_pk_mul_f32 v[6:7], v[6:7], v[48:49] op_sel_hi:[1,0]
	v_pk_mul_f32 v[8:9], v[8:9], v[48:49] op_sel_hi:[1,0]
	v_pk_mul_f32 v[10:11], v[10:11], v[48:49] op_sel_hi:[1,0]
	v_pk_mul_f32 v[12:13], v[12:13], v[48:49] op_sel_hi:[1,0]
	v_pk_mul_f32 v[14:15], v[14:15], v[48:49] op_sel_hi:[1,0]
	v_pk_mul_f32 v[30:31], v[30:31], v[48:49] op_sel_hi:[1,0]
	v_pk_mul_f32 v[32:33], v[32:33], v[48:49] op_sel_hi:[1,0]
	v_pk_mul_f32 v[34:35], v[34:35], v[48:49] op_sel_hi:[1,0]
	v_pk_mul_f32 v[36:37], v[36:37], v[48:49] op_sel_hi:[1,0]
	v_pk_mul_f32 v[38:39], v[38:39], v[48:49] op_sel_hi:[1,0]
	v_pk_mul_f32 v[40:41], v[40:41], v[48:49] op_sel_hi:[1,0]
	v_pk_mul_f32 v[42:43], v[42:43], v[48:49] op_sel_hi:[1,0]
	v_pk_mul_f32 v[44:45], v[44:45], v[48:49] op_sel_hi:[1,0]
	v_cvt_pk_bf16_f32 v0, v0, v1
	v_cvt_pk_bf16_f32 v1, v2, v3
	v_cvt_pk_bf16_f32 v2, v4, v5
	v_cvt_pk_bf16_f32 v3, v6, v7
	v_cvt_pk_bf16_f32 v4, v8, v9
	v_cvt_pk_bf16_f32 v5, v10, v11
	v_cvt_pk_bf16_f32 v6, v12, v13
	v_cvt_pk_bf16_f32 v7, v14, v15
	v_cvt_pk_bf16_f32 v8, v30, v31
	v_cvt_pk_bf16_f32 v9, v32, v33
	v_cvt_pk_bf16_f32 v10, v34, v35
	v_cvt_pk_bf16_f32 v11, v36, v37
	v_cvt_pk_bf16_f32 v12, v38, v39
	v_cvt_pk_bf16_f32 v13, v40, v41
	v_cvt_pk_bf16_f32 v14, v42, v43
	v_cvt_pk_bf16_f32 v15, v44, v45
	v_cvt_scalef32_pk32_fp6_bf16 v[30:35], v[0:15], 1.0
	global_store_dwordx4 v[46:47], v[30:33], off
	global_store_dwordx2 v[46:47], v[34:35], off offset:16
	s_and_saveexec_b64 s[42:43], s[40:41]
	s_cbranch_execz .LBB0_227
	v_readlane_b32 s44, v251, 42
	v_readlane_b32 s52, v251, 50
	v_readlane_b32 s53, v251, 51
	v_readlane_b32 s45, v251, 43
	v_readlane_b32 s46, v251, 44
	v_lshl_add_u64 v[0:1], v[20:21], 2, s[52:53]
	v_readlane_b32 s47, v251, 45
	v_readlane_b32 s48, v251, 46
	v_readlane_b32 s49, v251, 47
	v_readlane_b32 s50, v251, 48
	v_readlane_b32 s51, v251, 49
	v_readlane_b32 s54, v251, 52
	v_readlane_b32 s55, v251, 53
	v_readlane_b32 s56, v251, 54
	v_readlane_b32 s57, v251, 55
	v_readlane_b32 s58, v251, 56
	v_readlane_b32 s59, v251, 57
	global_store_dword v[0:1], v28, off
	s_branch .LBB0_227
; DEV int opaque_tid() { int t = (int)threadIdx.x; asm volatile("" : "+v"(t)); return t; }
; __device__ void quant_rows_fp4(const float* __restrict__ src, unsigned char* __restrict__ dst, float* __restrict__ scl, int nrows) {
;   const int tid = opaque_tid(), lane = tid & 63, w = tid >> 6;
;   for (int r = blockIdx.x * 4 + w; r < nrows; r += gridDim.x * 4) {
;     const float4* p = (const float4*)(src + (size_t)r * 1024 + lane * 16);
;     const float4 a = p[0], b = p[1], c = p[2], d = p[3];
;     float m = fmaxf(fmaxf(fmaxf(fabsf(a.x), fabsf(a.y)), fmaxf(fabsf(a.z), fabsf(a.w))), fmaxf(fmaxf(fabsf(b.x), fabsf(b.y)), fmaxf(fabsf(b.z), fabsf(b.w))));
;     m = fmaxf(m, fmaxf(fmaxf(fmaxf(fabsf(c.x), fabsf(c.y)), fmaxf(fabsf(c.z), fabsf(c.w))), fmaxf(fmaxf(fabsf(d.x), fabsf(d.y)), fmaxf(fabsf(d.z), fabsf(d.w)))));
.LBB0_230:
	s_waitcnt vmcnt(0)
	s_or_b64 exec, exec, s[0:1]
	v_mov_b32_e32 v1, v202
	v_readlane_b32 s0, v251, 62
	v_ashrrev_i32_e32 v0, 6, v1
	s_nop 0
	v_add_u32_e32 v0, s0, v0
	s_mov_b32 s0, 0x8000
	v_cmp_gt_i32_e32 vcc, s0, v0
	s_and_saveexec_b64 s[0:1], vcc
	s_cbranch_execz .LBB0_235
	v_and_b32_e32 v1, 63, v1
	v_readlane_b32 s40, v252, 12
	v_lshlrev_b32_e32 v176, 6, v1
	v_readlane_b32 s41, v252, 13
	v_readlane_b32 s42, v252, 14
	v_readlane_b32 s43, v252, 15
	v_readlane_b32 s44, v252, 16
	v_readlane_b32 s45, v252, 17
	v_readlane_b32 s46, v252, 18
	v_readlane_b32 s47, v252, 19
	v_readlane_b32 s48, v252, 20
	v_readlane_b32 s49, v252, 21
	v_readlane_b32 s50, v252, 22
	v_readlane_b32 s51, v252, 23
	v_readlane_b32 s52, v252, 24
	v_readlane_b32 s53, v252, 25
	v_readlane_b32 s54, v252, 26
	v_readlane_b32 s55, v252, 27
	v_lshl_add_u64 v[2:3], s[48:49], 0, v[176:177]
	v_readlane_b32 s40, v251, 42
	v_and_b32_e32 v4, 64, v212
	v_readlane_b32 s41, v251, 43
	v_add_u32_e32 v11, 64, v4
	v_lshlrev_b32_e32 v176, 3, v1
	v_cmp_eq_u32_e64 s[40:41], 0, v1
	v_xor_b32_e32 v1, 1, v212
	v_cmp_lt_i32_e32 vcc, v1, v11
	v_readlane_b32 s46, v251, 48
	v_readlane_b32 s47, v251, 49
	v_cndmask_b32_e32 v1, v212, v1, vcc
	v_lshlrev_b32_e32 v6, 2, v1
	v_xor_b32_e32 v1, 2, v212
	v_cmp_lt_i32_e32 vcc, v1, v11
	v_readlane_b32 s4, v248, 34
	v_lshl_add_u64 v[4:5], s[46:47], 0, v[176:177]
	v_cndmask_b32_e32 v1, v212, v1, vcc
	v_lshlrev_b32_e32 v7, 2, v1
	v_xor_b32_e32 v1, 4, v212
	v_cmp_lt_i32_e32 vcc, v1, v11
	s_lshl_b32 s2, s4, 2
	s_mov_b64 s[38:39], 0
	v_cndmask_b32_e32 v1, v212, v1, vcc
	v_lshlrev_b32_e32 v8, 2, v1
	v_xor_b32_e32 v1, 8, v212
	v_cmp_lt_i32_e32 vcc, v1, v11
	v_readlane_b32 s42, v251, 44
	v_readlane_b32 s43, v251, 45
	v_cndmask_b32_e32 v1, v212, v1, vcc
	v_lshlrev_b32_e32 v9, 2, v1
	v_xor_b32_e32 v1, 16, v212
	v_cmp_lt_i32_e32 vcc, v1, v11
	v_readlane_b32 s44, v251, 46
	v_readlane_b32 s45, v251, 47
	v_cndmask_b32_e32 v1, v212, v1, vcc
	v_lshlrev_b32_e32 v10, 2, v1
	v_xor_b32_e32 v1, 32, v212
	v_cmp_lt_i32_e32 vcc, v1, v11
	v_readlane_b32 s48, v251, 50
	v_readlane_b32 s49, v251, 51
	v_cndmask_b32_e32 v1, v212, v1, vcc
	v_lshlrev_b32_e32 v11, 2, v1
	v_readlane_b32 s50, v251, 52
	v_readlane_b32 s51, v251, 53
	v_readlane_b32 s52, v251, 54
	v_readlane_b32 s53, v251, 55
	v_readlane_b32 s54, v251, 56
	v_readlane_b32 s55, v251, 57
	v_readlane_b32 s5, v248, 35
	v_ashrrev_i32_e32 v1, 31, v0
	v_lshlrev_b64 v[96:97], 12, v[0:1]
	v_lshl_add_u64 v[96:97], v[2:3], 0, v[96:97]
	global_load_dwordx4 v[64:67], v[96:97], off offset:48
	global_load_dwordx4 v[68:71], v[96:97], off offset:32
	global_load_dwordx4 v[72:75], v[96:97], off offset:16
	global_load_dwordx4 v[76:79], v[96:97], off
	s_waitcnt vmcnt(0)
	s_branch .Lq4a_copy
.LBB0_232:
	s_or_b64 exec, exec, s[42:43]
	v_add_u32_e32 v0, s2, v0
	s_movk_i32 s4, 0x7fff
	v_cmp_lt_i32_e32 vcc, s4, v0
	s_or_b64 s[38:39], vcc, s[38:39]
	s_andn2_b64 exec, exec, s[38:39]
	s_cbranch_execz .LBB0_235
.LBB0_233:
	s_waitcnt vmcnt(2)
; __device__ void quant_rows_fp4(const float* __restrict__ src, unsigned char* __restrict__ dst, float* __restrict__ scl, int nrows) {
;     ...
;   for (int r = blockIdx.x * 4 + w; r < nrows; r += gridDim.x * 4) {
;     const float4* p = (const float4*)(src + (size_t)r * 1024 + lane * 16);
;     const float4 a = p[0], b = p[1], c = p[2], d = p[3];
;     float m = fmaxf(fmaxf(fmaxf(fabsf(a.x), fabsf(a.y)), fmaxf(fabsf(a.z), fabsf(a.w))), fmaxf(fmaxf(fabsf(b.x), fabsf(b.y)), fmaxf(fabsf(b.z), fabsf(b.w))));
;     m = fmaxf(m, fmaxf(fmaxf(fmaxf(fabsf(c.x), fabsf(c.y)), fmaxf(fabsf(c.z), fabsf(c.w))), fmaxf(fmaxf(fabsf(d.x), fabsf(d.y)), fmaxf(fabsf(d.z), fabsf(d.w)))));
; #pragma unroll
;     for (int o = 1; o < 64; o <<= 1) m = fmaxf(m, __shfl_xor(m, o, 64));
;     const float sc = (m > 0.f) ? m * (1.f / 6.f) : 1.f;
;     const float inv = 1.f / sc;
;     unsigned q0 = 0u, q1 = 0u;
;     q0 = __builtin_amdgcn_cvt_scalef32_pk_fp4_f32(q0, a.x * inv, a.y * inv, 1.0f, 0);
;     q0 = __builtin_amdgcn_cvt_scalef32_pk_fp4_f32(q0, a.z * inv, a.w * inv, 1.0f, 1);
;     q0 = __builtin_amdgcn_cvt_scalef32_pk_fp4_f32(q0, b.x * inv, b.y * inv, 1.0f, 2);
;     q0 = __builtin_amdgcn_cvt_scalef32_pk_fp4_f32(q0, b.z * inv, b.w * inv, 1.0f, 3);
;     q1 = __builtin_amdgcn_cvt_scalef32_pk_fp4_f32(q1, c.x * inv, c.y * inv, 1.0f, 0);
;     q1 = __builtin_amdgcn_cvt_scalef32_pk_fp4_f32(q1, c.z * inv, c.w * inv, 1.0f, 1);
;     q1 = __builtin_amdgcn_cvt_scalef32_pk_fp4_f32(q1, d.x * inv, d.y * inv, 1.0f, 2);
;     q1 = __builtin_amdgcn_cvt_scalef32_pk_fp4_f32(q1, d.z * inv, d.w * inv, 1.0f, 3);
;     uint2 o2; o2.x = q0; o2.y = q1;
;     *(uint2*)(dst + (size_t)r * 512 + lane * 8) = o2;
;     if (lane == 0) scl[r] = sc;
;   }
.Lq4a_copy:
	v_pk_mov_b32 v[14:15], v[64:65], v[64:65] op_sel:[0,1]
	v_pk_mov_b32 v[16:17], v[66:67], v[66:67] op_sel:[0,1]
	v_pk_mov_b32 v[18:19], v[68:69], v[68:69] op_sel:[0,1]
	v_pk_mov_b32 v[20:21], v[70:71], v[70:71] op_sel:[0,1]
	v_pk_mov_b32 v[22:23], v[72:73], v[72:73] op_sel:[0,1]
	v_pk_mov_b32 v[24:25], v[74:75], v[74:75] op_sel:[0,1]
	v_pk_mov_b32 v[26:27], v[76:77], v[76:77] op_sel:[0,1]
	v_pk_mov_b32 v[28:29], v[78:79], v[78:79] op_sel:[0,1]
	v_add_u32_e32 v96, s2, v0
	v_min_i32_e32 v96, 0x7fff, v96
	v_ashrrev_i32_e32 v97, 31, v96
	v_lshlrev_b64 v[96:97], 12, v[96:97]
	v_lshl_add_u64 v[96:97], v[2:3], 0, v[96:97]
	global_load_dwordx4 v[64:67], v[96:97], off offset:48
	global_load_dwordx4 v[68:71], v[96:97], off offset:32
	global_load_dwordx4 v[72:75], v[96:97], off offset:16
	global_load_dwordx4 v[76:79], v[96:97], off
	v_ashrrev_i32_e32 v1, 31, v0
	v_max_f32_e64 v33, |v16|, |v16|
	v_max_f32_e64 v31, |v18|, |v18|
	v_max_f32_e64 v30, |v24|, |v24|
	v_max_f32_e64 v12, |v29|, |v29|
	v_max_f32_e64 v13, |v28|, |v28|
	v_max_f32_e32 v12, v13, v12
	v_max_f32_e64 v13, |v25|, |v25|
	v_max_f32_e32 v13, v30, v13
	v_max_f32_e64 v30, |v19|, |v19|
	v_max_f32_e32 v30, v31, v30
	v_max_f32_e64 v31, |v21|, |v21|
	v_max_f32_e64 v32, |v20|, |v20|
	v_max_f32_e32 v31, v32, v31
	v_max_f32_e64 v32, |v17|, |v17|
	v_max_f32_e32 v32, v33, v32
	v_max3_f32 v32, |v14|, |v15|, v32
	v_max3_f32 v12, |v26|, |v27|, v12
	v_max3_f32 v13, |v22|, |v23|, v13
	v_max3_f32 v30, v30, v31, v32
	v_max3_f32 v12, v12, v13, v30
	ds_bpermute_b32 v13, v6, v12
	s_waitcnt lgkmcnt(0)
	v_max_f32_e32 v13, v13, v13
	v_max_f32_e32 v12, v12, v13
	ds_bpermute_b32 v13, v7, v12
	s_waitcnt lgkmcnt(0)
	v_max_f32_e32 v13, v13, v13
	v_max_f32_e32 v12, v12, v13
	ds_bpermute_b32 v13, v8, v12
	s_waitcnt lgkmcnt(0)
	v_max_f32_e32 v13, v13, v13
	v_max_f32_e32 v12, v12, v13
	ds_bpermute_b32 v13, v9, v12
	s_waitcnt lgkmcnt(0)
	v_max_f32_e32 v13, v13, v13
	v_max_f32_e32 v12, v12, v13
	ds_bpermute_b32 v13, v10, v12
	s_waitcnt lgkmcnt(0)
	v_max_f32_e32 v13, v13, v13
	v_max_f32_e32 v12, v12, v13
	ds_bpermute_b32 v13, v11, v12
	s_waitcnt lgkmcnt(0)
	v_max_f32_e32 v13, v13, v13
	v_max_f32_e32 v12, v12, v13
	v_cmp_lt_f32_e32 vcc, 0, v12
	v_mul_f32_e32 v12, 0x3e2aaaab, v12
	s_nop 0
	v_cndmask_b32_e32 v12, 1.0, v12, vcc
	v_div_scale_f32 v13, s[4:5], v12, v12, 1.0
	v_rcp_f32_e32 v30, v13
	s_nop 0
	v_fma_f32 v31, -v13, v30, 1.0
	v_fmac_f32_e32 v30, v31, v30
	v_div_scale_f32 v31, vcc, 1.0, v12, 1.0
	v_mul_f32_e32 v32, v31, v30
	v_fma_f32 v33, -v13, v32, v31
	v_fmac_f32_e32 v32, v33, v30
	v_fma_f32 v13, -v13, v32, v31
	v_div_fmas_f32 v13, v13, v30, v32
	v_div_fixup_f32 v13, v13, v12, 1.0
	v_mul_f32_e32 v30, v26, v13
	v_mul_f32_e32 v27, v27, v13
	v_mov_b32_e32 v26, v177
	v_cvt_scalef32_pk_fp4_f32 v26, v30, v27, 1.0
	v_mul_f32_e32 v27, v28, v13
	v_mul_f32_e32 v28, v29, v13
	v_cvt_scalef32_pk_fp4_f32 v26, v27, v28, 1.0 op_sel:[0,0,1,0]
	v_mul_f32_e32 v18, v18, v13
	v_mul_f32_e32 v19, v19, v13
	v_mov_b32_e32 v27, v177
	v_cvt_scalef32_pk_fp4_f32 v27, v18, v19, 1.0
	v_mul_f32_e32 v18, v20, v13
	v_mul_f32_e32 v19, v21, v13
	v_mul_f32_e32 v22, v22, v13
	v_mul_f32_e32 v23, v23, v13
	v_cvt_scalef32_pk_fp4_f32 v27, v18, v19, 1.0 op_sel:[0,0,1,0]
	v_mul_f32_e32 v14, v14, v13
	v_mul_f32_e32 v15, v15, v13
	v_cvt_scalef32_pk_fp4_f32 v26, v22, v23, 1.0 op_sel:[0,0,0,1]
	v_mul_f32_e32 v22, v24, v13
	v_mul_f32_e32 v23, v25, v13
	v_cvt_scalef32_pk_fp4_f32 v27, v14, v15, 1.0 op_sel:[0,0,0,1]
	v_mul_f32_e32 v14, v16, v13
	v_mul_f32_e32 v13, v17, v13
	v_cvt_scalef32_pk_fp4_f32 v27, v14, v13, 1.0 op_sel:[0,0,1,1]
	v_lshlrev_b64 v[14:15], 9, v[0:1]
	v_cvt_scalef32_pk_fp4_f32 v26, v22, v23, 1.0 op_sel:[0,0,1,1]
	v_lshl_add_u64 v[14:15], v[4:5], 0, v[14:15]
	global_store_dwordx2 v[14:15], v[26:27], off
	s_and_saveexec_b64 s[42:43], s[40:41]
	s_cbranch_execz .LBB0_232
	v_readlane_b32 s44, v251, 42
	v_readlane_b32 s54, v251, 52
	v_readlane_b32 s55, v251, 53
	v_readlane_b32 s45, v251, 43
	v_readlane_b32 s46, v251, 44
	v_lshl_add_u64 v[14:15], v[0:1], 2, s[54:55]
	v_readlane_b32 s47, v251, 45
	v_readlane_b32 s48, v251, 46
	v_readlane_b32 s49, v251, 47
	v_readlane_b32 s50, v251, 48
	v_readlane_b32 s51, v251, 49
	v_readlane_b32 s52, v251, 50
	v_readlane_b32 s53, v251, 51
	v_readlane_b32 s56, v251, 54
	v_readlane_b32 s57, v251, 55
	v_readlane_b32 s58, v251, 56
	v_readlane_b32 s59, v251, 57
	global_store_dword v[14:15], v12, off
	s_branch .LBB0_232
.LBB0_235:
	s_waitcnt vmcnt(0)
	s_or_b64 exec, exec, s[0:1]

; DEV int opaque_tid() { int t = (int)threadIdx.x; asm volatile("" : "+v"(t)); return t; }
; __device__ void quant_rows_fp6(const float* __restrict__ src, unsigned char* __restrict__ dst, float* __restrict__ scl, int nrows) {
;   const int tid = opaque_tid(), lane = tid & 63, w = tid >> 6;
;   const int l32 = lane & 31, hf = lane >> 5;
;   for (int rp = blockIdx.x * 4 + w; rp < nrows / 2; rp += gridDim.x * 4) {
;     const int r = rp * 2 + hf;
;     const float4* p = (const float4*)(src + (size_t)r * 1024 + l32 * 32);
;     float v[32];
; #pragma unroll
;     for (int i = 0; i < 8; ++i) { const float4 t = p[i]; v[4 * i] = t.x; v[4 * i + 1] = t.y; v[4 * i + 2] = t.z; v[4 * i + 3] = t.w; }
.LBB0_270:
	v_readlane_b32 s0, v248, 7
	v_readlane_b32 s1, v248, 8
	s_andn2_b64 vcc, exec, s[0:1]
	s_cbranch_vccnz .LBB0_282
	v_mov_b32_e32 v1, v202
	v_readlane_b32 s0, v251, 62
	v_ashrrev_i32_e32 v0, 6, v1
	s_nop 0
	v_add_u32_e32 v22, s0, v0
	v_cmp_gt_i32_e32 vcc, s97, v22
	s_and_saveexec_b64 s[0:1], vcc
	s_cbranch_execz .LBB0_276
	v_bfe_u32 v2, v1, 5, 1
	v_and_b32_e32 v1, 31, v1
	v_readlane_b32 s40, v252, 12
	v_lshlrev_b32_e32 v176, 7, v1
	v_readlane_b32 s41, v252, 13
	v_readlane_b32 s42, v252, 14
	v_readlane_b32 s43, v252, 15
	v_readlane_b32 s44, v252, 16
	v_readlane_b32 s45, v252, 17
	v_readlane_b32 s46, v252, 18
	v_readlane_b32 s47, v252, 19
	v_readlane_b32 s48, v252, 20
	v_readlane_b32 s49, v252, 21
	v_readlane_b32 s50, v252, 22
	v_readlane_b32 s51, v252, 23
	v_readlane_b32 s52, v252, 24
	v_readlane_b32 s53, v252, 25
	v_readlane_b32 s54, v252, 26
	v_readlane_b32 s55, v252, 27
	v_lshl_add_u64 v[16:17], s[46:47], 0, v[176:177]
	v_readlane_b32 s40, v251, 42
	v_and_b32_e32 v3, 64, v212
	v_readlane_b32 s41, v251, 43
	v_add_u32_e32 v3, 64, v3
	v_mul_u32_u24_e32 v176, 24, v1
	v_cmp_eq_u32_e64 s[40:41], 0, v1
	v_xor_b32_e32 v1, 1, v212
	v_cmp_lt_i32_e32 vcc, v1, v3
	v_readlane_b32 s4, v248, 34
	v_readlane_b32 s44, v251, 46
	v_cndmask_b32_e32 v1, v212, v1, vcc
	v_lshlrev_b32_e32 v23, 2, v1
	v_xor_b32_e32 v1, 2, v212
	v_cmp_lt_i32_e32 vcc, v1, v3
	v_readlane_b32 s45, v251, 47
	s_mov_b32 s6, s4
	v_cndmask_b32_e32 v1, v212, v1, vcc
	v_lshlrev_b32_e32 v24, 2, v1
	v_xor_b32_e32 v1, 4, v212
	v_cmp_lt_i32_e32 vcc, v1, v3
	s_lshl_b32 s2, s4, 2
	v_lshlrev_b32_e32 v0, 1, v0
	v_cndmask_b32_e32 v1, v212, v1, vcc
	v_lshlrev_b32_e32 v25, 2, v1
	v_xor_b32_e32 v1, 8, v212
	v_cmp_lt_i32_e32 vcc, v1, v3
	v_readlane_b32 s4, v249, 2
	v_lshl_add_u64 v[18:19], s[44:45], 0, v[176:177]
	v_cndmask_b32_e32 v1, v212, v1, vcc
	v_lshlrev_b32_e32 v26, 2, v1
	v_xor_b32_e32 v1, 16, v212
	v_cmp_lt_i32_e32 vcc, v1, v3
	v_add3_u32 v20, s4, v0, v2
	s_lshl_b32 s4, s6, 3
	v_cndmask_b32_e32 v1, v212, v1, vcc
	v_lshlrev_b32_e32 v27, 2, v1
	s_mov_b64 s[38:39], 0
	v_readlane_b32 s42, v251, 44
	v_readlane_b32 s43, v251, 45
	v_readlane_b32 s46, v251, 48
	v_readlane_b32 s47, v251, 49
	v_readlane_b32 s48, v251, 50
	v_readlane_b32 s49, v251, 51
	v_readlane_b32 s50, v251, 52
	v_readlane_b32 s51, v251, 53
	v_readlane_b32 s52, v251, 54
	v_readlane_b32 s53, v251, 55
	v_readlane_b32 s54, v251, 56
	v_readlane_b32 s55, v251, 57
	v_readlane_b32 s5, v248, 35
	v_ashrrev_i32_e32 v21, 31, v20
	v_lshlrev_b64 v[96:97], 12, v[20:21]
	v_lshl_add_u64 v[96:97], v[16:17], 0, v[96:97]
	global_load_dwordx4 v[64:67], v[96:97], off
	global_load_dwordx4 v[68:71], v[96:97], off offset:16
	global_load_dwordx4 v[72:75], v[96:97], off offset:32
	global_load_dwordx4 v[76:79], v[96:97], off offset:48
	global_load_dwordx4 v[80:83], v[96:97], off offset:64
	global_load_dwordx4 v[84:87], v[96:97], off offset:80
	global_load_dwordx4 v[88:91], v[96:97], off offset:96
	global_load_dwordx4 v[92:95], v[96:97], off offset:112
	s_waitcnt vmcnt(0)
	s_branch .Lq6b_copy

; __device__ void quant_rows_fp4(const float* __restrict__ src, unsigned char* __restrict__ dst, float* __restrict__ scl, int nrows) {
;     ...
;   for (int r = blockIdx.x * 4 + w; r < nrows; r += gridDim.x * 4) {
;     const float4* p = (const float4*)(src + (size_t)r * 1024 + lane * 16);
;     const float4 a = p[0], b = p[1], c = p[2], d = p[3];
;     float m = fmaxf(fmaxf(fmaxf(fabsf(a.x), fabsf(a.y)), fmaxf(fabsf(a.z), fabsf(a.w))), fmaxf(fmaxf(fabsf(b.x), fabsf(b.y)), fmaxf(fabsf(b.z), fabsf(b.w))));
;     m = fmaxf(m, fmaxf(fmaxf(fmaxf(fabsf(c.x), fabsf(c.y)), fmaxf(fabsf(c.z), fabsf(c.w))), fmaxf(fmaxf(fabsf(d.x), fabsf(d.y)), fmaxf(fabsf(d.z), fabsf(d.w)))));
; #pragma unroll
;     for (int o = 1; o < 64; o <<= 1) m = fmaxf(m, __shfl_xor(m, o, 64));
;     const float sc = (m > 0.f) ? m * (1.f / 6.f) : 1.f;
;     const float inv = 1.f / sc;
;     unsigned q0 = 0u, q1 = 0u;
;     q0 = __builtin_amdgcn_cvt_scalef32_pk_fp4_f32(q0, a.x * inv, a.y * inv, 1.0f, 0);
;     q0 = __builtin_amdgcn_cvt_scalef32_pk_fp4_f32(q0, a.z * inv, a.w * inv, 1.0f, 1);
;     q0 = __builtin_amdgcn_cvt_scalef32_pk_fp4_f32(q0, b.x * inv, b.y * inv, 1.0f, 2);
;     q0 = __builtin_amdgcn_cvt_scalef32_pk_fp4_f32(q0, b.z * inv, b.w * inv, 1.0f, 3);
;     q1 = __builtin_amdgcn_cvt_scalef32_pk_fp4_f32(q1, c.x * inv, c.y * inv, 1.0f, 0);
;     q1 = __builtin_amdgcn_cvt_scalef32_pk_fp4_f32(q1, c.z * inv, c.w * inv, 1.0f, 1);
;     q1 = __builtin_amdgcn_cvt_scalef32_pk_fp4_f32(q1, d.x * inv, d.y * inv, 1.0f, 2);
;     q1 = __builtin_amdgcn_cvt_scalef32_pk_fp4_f32(q1, d.z * inv, d.w * inv, 1.0f, 3);
;     uint2 o2; o2.x = q0; o2.y = q1;
;     *(uint2*)(dst + (size_t)r * 512 + lane * 8) = o2;
;     if (lane == 0) scl[r] = sc;
;   }
.LBB0_278:
	s_or_b64 exec, exec, s[42:43]
	v_add_u32_e32 v0, s2, v0
	s_movk_i32 s4, 0x7fff
	v_cmp_lt_i32_e32 vcc, s4, v0
	s_or_b64 s[38:39], vcc, s[38:39]
	s_andn2_b64 exec, exec, s[38:39]
	s_cbranch_execz .LBB0_281
.LBB0_279:
	s_waitcnt vmcnt(2)
